# sliding-window step loop: next block's staged K/V rows written to the idle LDS buffer before the exp/PV section (as in the selected loop); on top of version 48
# speedup vs baseline: 1.0034x; 1.0034x over previous
.LBB0_1495:
	s_add_i32 s98, s12, 2
	s_cmp_lt_i32 s98, s15
	s_cbranch_scc1 .Lmy_ww1
	s_waitcnt vmcnt(2)
	ds_write_b128 v159, v[18:21]
	ds_write_b128 v159, v[22:25] offset:10240
.Lmy_ww1:
	v_exp_f32_e32 v78, v78
	v_exp_f32_e32 v79, v79
	v_exp_f32_e32 v80, v80
	v_exp_f32_e32 v81, v81
	v_exp_f32_e32 v98, v98
	v_exp_f32_e32 v99, v99
	v_exp_f32_e32 v100, v100
	v_exp_f32_e32 v101, v101
	v_exp_f32_e32 v82, v82
	v_exp_f32_e32 v83, v83
	v_exp_f32_e32 v84, v84
	v_exp_f32_e32 v85, v85
	v_exp_f32_e32 v86, v86
	v_exp_f32_e32 v87, v87
	v_cvt_pk_bf16_f32 v114, v78, v79
	ds_read_b64_tr_b16 v[78:79], v170 offset:0
	v_exp_f32_e32 v88, v88
	v_exp_f32_e32 v89, v89
	v_cvt_pk_bf16_f32 v115, v80, v81
	ds_read_b64_tr_b16 v[80:81], v170 offset:2560
	v_exp_f32_e32 v108, v92
	v_exp_f32_e32 v109, v93
	v_cvt_pk_bf16_f32 v92, v98, v99
	v_cvt_pk_bf16_f32 v93, v100, v101
	v_exp_f32_e32 v98, v74
	v_exp_f32_e32 v99, v75
	v_exp_f32_e32 v100, v76
	v_cvt_pk_bf16_f32 v76, v82, v83
	ds_read_b64_tr_b16 v[82:83], v170 offset:32
	v_exp_f32_e32 v101, v77
	v_cvt_pk_bf16_f32 v77, v84, v85
	ds_read_b64_tr_b16 v[84:85], v170 offset:2592
	v_exp_f32_e32 v102, v102
	v_exp_f32_e32 v103, v103
	v_cvt_pk_bf16_f32 v74, v86, v87
	ds_read_b64_tr_b16 v[86:87], v170 offset:64
	v_exp_f32_e32 v104, v104
	v_exp_f32_e32 v105, v105
	v_cvt_pk_bf16_f32 v75, v88, v89
	ds_read_b64_tr_b16 v[88:89], v170 offset:2624
	v_exp_f32_e32 v94, v94
	v_exp_f32_e32 v95, v95
	v_exp_f32_e32 v96, v96
	v_exp_f32_e32 v97, v97
	v_exp_f32_e32 v106, v90
	v_exp_f32_e32 v107, v91
	v_cvt_pk_bf16_f32 v116, v98, v99
	ds_read_b64_tr_b16 v[98:99], v170 offset:96
	v_cvt_pk_bf16_f32 v117, v100, v101
	ds_read_b64_tr_b16 v[100:101], v170 offset:2656
	v_cvt_pk_bf16_f32 v90, v102, v103
	ds_read_b64_tr_b16 v[102:103], v170 offset:5120
	v_cvt_pk_bf16_f32 v91, v104, v105
	ds_read_b64_tr_b16 v[104:105], v170 offset:7680
	v_cvt_pk_bf16_f32 v94, v94, v95
	v_cvt_pk_bf16_f32 v95, v96, v97
	v_cvt_pk_bf16_f32 v96, v106, v107
	ds_read_b64_tr_b16 v[106:107], v170 offset:5152
	v_cvt_pk_bf16_f32 v97, v108, v109
	ds_read_b64_tr_b16 v[108:109], v170 offset:7712
	ds_read_b64_tr_b16 v[110:111], v170 offset:5184
	ds_read_b64_tr_b16 v[112:113], v170 offset:7744
	ds_read_b64_tr_b16 v[118:119], v170 offset:5216
	ds_read_b64_tr_b16 v[120:121], v170 offset:7776
	s_waitcnt lgkmcnt(8)
	s_setprio 1
	s_mov_b32 s82, s80
	s_mov_b32 s83, s80
	s_mov_b32 s81, s80
	v_mov_b64_e32 v[124:125], s[82:83]
	v_mov_b64_e32 v[122:123], s[80:81]
	s_waitcnt lgkmcnt(0)
	v_mfma_f32_16x16x32_bf16 v[34:37], v[78:81], v[90:93], v[34:37]
	v_mfma_f32_16x16x32_bf16 v[54:57], v[78:81], v[74:77], v[54:57]
	v_mfma_f32_16x16x32_bf16 v[38:41], v[82:85], v[90:93], v[38:41]
	v_mfma_f32_16x16x32_bf16 v[58:61], v[82:85], v[74:77], v[58:61]
	v_mfma_f32_16x16x32_bf16 v[26:29], v[86:89], v[90:93], v[26:29]
	v_mfma_f32_16x16x32_bf16 v[42:45], v[86:89], v[74:77], v[42:45]
	v_mfma_f32_16x16x32_bf16 v[30:33], v[98:101], v[90:93], v[30:33]
	v_mfma_f32_16x16x32_bf16 v[46:49], v[98:101], v[74:77], v[46:49]
	v_mfma_f32_16x16x32_bf16 v[50:53], v[122:125], v[90:93], v[50:53]
	v_mfma_f32_16x16x32_bf16 v[62:65], v[122:125], v[74:77], v[62:65]
	v_mfma_f32_16x16x32_bf16 v[74:77], v[102:105], v[94:97], v[34:37]
	v_mfma_f32_16x16x32_bf16 v[78:81], v[102:105], v[114:117], v[54:57]
	v_mfma_f32_16x16x32_bf16 v[82:85], v[106:109], v[94:97], v[38:41]
	v_mfma_f32_16x16x32_bf16 v[86:89], v[106:109], v[114:117], v[58:61]
	v_mfma_f32_16x16x32_bf16 v[90:93], v[110:113], v[94:97], v[26:29]
	v_mfma_f32_16x16x32_bf16 v[98:101], v[110:113], v[114:117], v[42:45]
	v_mfma_f32_16x16x32_bf16 v[106:109], v[118:121], v[94:97], v[30:33]
	v_mfma_f32_16x16x32_bf16 v[110:113], v[118:121], v[114:117], v[46:49]
	v_mfma_f32_16x16x32_bf16 v[102:105], v[122:125], v[94:97], v[50:53]
	v_mfma_f32_16x16x32_bf16 v[94:97], v[122:125], v[114:117], v[62:65]
	s_setprio 0
	s_add_i32 s16, s12, 2
	s_branch .LBB0_1497

.LBB0_1500:
	s_cmp_lt_i32 s13, s15
	s_cbranch_scc1 .Lmy_ww2
	s_waitcnt vmcnt(2)
	ds_write_b128 v159, v[66:69] offset:20480
	ds_write_b128 v159, v[70:73] offset:30720
.Lmy_ww2:
	v_exp_f32_e32 v138, v138
	v_exp_f32_e32 v139, v139
	v_exp_f32_e32 v140, v140
	v_exp_f32_e32 v141, v141
	v_exp_f32_e32 v122, v122
	v_exp_f32_e32 v123, v123
	v_exp_f32_e32 v124, v124
	v_exp_f32_e32 v125, v125
	v_exp_f32_e32 v126, v126
	v_exp_f32_e32 v127, v127
	v_exp_f32_e32 v128, v128
	v_exp_f32_e32 v129, v129
	v_exp_f32_e32 v182, v132
	v_exp_f32_e32 v183, v133
	v_cvt_pk_bf16_f32 v132, v138, v139
	v_cvt_pk_bf16_f32 v133, v140, v141
	v_exp_f32_e32 v118, v118
	v_exp_f32_e32 v119, v119
	v_exp_f32_e32 v120, v120
	v_exp_f32_e32 v121, v121
	v_exp_f32_e32 v138, v114
	v_exp_f32_e32 v139, v115
	v_exp_f32_e32 v140, v116
	v_cvt_pk_bf16_f32 v116, v122, v123
	ds_read_b64_tr_b16 v[122:123], v168 offset:0
	v_exp_f32_e32 v141, v117
	v_cvt_pk_bf16_f32 v117, v124, v125
	ds_read_b64_tr_b16 v[124:125], v168 offset:2560
	v_exp_f32_e32 v142, v142
	v_exp_f32_e32 v143, v143
	v_cvt_pk_bf16_f32 v114, v126, v127
	ds_read_b64_tr_b16 v[126:127], v168 offset:32
	v_exp_f32_e32 v144, v144
	v_exp_f32_e32 v145, v145
	v_cvt_pk_bf16_f32 v115, v128, v129
	ds_read_b64_tr_b16 v[128:129], v168 offset:2592
	v_exp_f32_e32 v134, v134
	v_exp_f32_e32 v135, v135
	v_exp_f32_e32 v136, v136
	v_exp_f32_e32 v137, v137
	v_exp_f32_e32 v180, v130
	v_exp_f32_e32 v181, v131
	v_cvt_pk_bf16_f32 v118, v118, v119
	v_cvt_pk_bf16_f32 v119, v120, v121
	v_cvt_pk_bf16_f32 v120, v138, v139
	ds_read_b64_tr_b16 v[138:139], v168 offset:64
	v_cvt_pk_bf16_f32 v121, v140, v141
	ds_read_b64_tr_b16 v[140:141], v168 offset:2624
	v_cvt_pk_bf16_f32 v130, v142, v143
	ds_read_b64_tr_b16 v[142:143], v168 offset:96
	v_cvt_pk_bf16_f32 v131, v144, v145
	ds_read_b64_tr_b16 v[144:145], v168 offset:2656
	v_cvt_pk_bf16_f32 v134, v134, v135
	v_cvt_pk_bf16_f32 v135, v136, v137
	v_cvt_pk_bf16_f32 v136, v180, v181
	ds_read_b64_tr_b16 v[180:181], v168 offset:5120
	v_cvt_pk_bf16_f32 v137, v182, v183
	ds_read_b64_tr_b16 v[182:183], v168 offset:7680
	ds_read_b64_tr_b16 v[184:185], v168 offset:5152
	ds_read_b64_tr_b16 v[186:187], v168 offset:7712
	ds_read_b64_tr_b16 v[188:189], v168 offset:5184
	ds_read_b64_tr_b16 v[190:191], v168 offset:7744
	ds_read_b64_tr_b16 v[192:193], v168 offset:5216
	ds_read_b64_tr_b16 v[194:195], v168 offset:7776
	s_waitcnt lgkmcnt(8)
	s_setprio 1
	s_mov_b32 s82, s80
	s_mov_b32 s83, s80
	v_mfma_f32_16x16x32_bf16 v[34:37], v[122:125], v[130:133], v[34:37]
	s_mov_b32 s81, s80
	s_waitcnt lgkmcnt(0)
	v_mfma_f32_16x16x32_bf16 v[54:57], v[122:125], v[114:117], v[54:57]
	v_mov_b64_e32 v[124:125], s[82:83]
	v_mov_b64_e32 v[122:123], s[80:81]
	v_mfma_f32_16x16x32_bf16 v[38:41], v[126:129], v[130:133], v[38:41]
	v_mfma_f32_16x16x32_bf16 v[58:61], v[126:129], v[114:117], v[58:61]
	v_mfma_f32_16x16x32_bf16 v[26:29], v[138:141], v[130:133], v[26:29]
	v_mfma_f32_16x16x32_bf16 v[42:45], v[138:141], v[114:117], v[42:45]
	v_mfma_f32_16x16x32_bf16 v[30:33], v[142:145], v[130:133], v[30:33]
	v_mfma_f32_16x16x32_bf16 v[46:49], v[142:145], v[114:117], v[46:49]
	v_mfma_f32_16x16x32_bf16 v[50:53], v[122:125], v[130:133], v[50:53]
	v_mfma_f32_16x16x32_bf16 v[62:65], v[122:125], v[114:117], v[62:65]
	v_mfma_f32_16x16x32_bf16 v[34:37], v[180:183], v[134:137], v[34:37]
	v_mfma_f32_16x16x32_bf16 v[54:57], v[180:183], v[118:121], v[54:57]
	v_mfma_f32_16x16x32_bf16 v[38:41], v[184:187], v[134:137], v[38:41]
	v_mfma_f32_16x16x32_bf16 v[58:61], v[184:187], v[118:121], v[58:61]
	v_mfma_f32_16x16x32_bf16 v[26:29], v[188:191], v[134:137], v[26:29]
	v_mfma_f32_16x16x32_bf16 v[42:45], v[188:191], v[118:121], v[42:45]
	v_mfma_f32_16x16x32_bf16 v[30:33], v[192:195], v[134:137], v[30:33]
	v_mfma_f32_16x16x32_bf16 v[46:49], v[192:195], v[118:121], v[46:49]
	v_mfma_f32_16x16x32_bf16 v[50:53], v[122:125], v[134:137], v[50:53]
	v_mfma_f32_16x16x32_bf16 v[62:65], v[122:125], v[118:121], v[62:65]
	s_setprio 0
	s_branch .LBB0_1503
